# m3 acquire: wait for the cache invalidate to complete before the block barrier (release/acquire recipe hardening)
# speedup vs baseline: 1.0052x; 1.0026x over previous
.Lm3acq_ok:
	buffer_inv sc1
	s_waitcnt vmcnt(0)
